# speedup vs baseline: 1.0078x; 1.0078x over previous
; __device__ __forceinline__ void finishSM(f32x16& p0, f32x16& p1, float alpha, float& l_reg, bf16x8& pa0, bf16x8& pa1, bf16x8& pa2, bf16x8& pa3) {
; #pragma unroll
;   for (int r = 0; r < 16; ++r) p1[r] = __builtin_amdgcn_exp2f(p1[r]);
;   float ps = 0;
; #pragma unroll
;   for (int r = 0; r < 16; ++r) ps += p0[r];
; #pragma unroll
;   for (int r = 0; r < 16; ++r) ps += p1[r];
;   { auto rr = __builtin_amdgcn_permlane32_swap(__float_as_uint(ps), __float_as_uint(ps), false, false);
;     ps = __uint_as_float(rr[0]) + __uint_as_float(rr[1]); }
;   l_reg = l_reg * alpha + ps;
;     ...
;   PK4(p0, 0, pa0); PK4(p0, 8, pa1); PK4(p1, 0, pa2); PK4(p1, 8, pa3);
; template <int BUFOFF>
; __device__ __forceinline__ void qkt_mla(f32x16& p0, f32x16& p1, const int* ka, const bf16x8* qr, const char* qlds) {
;   typedef __attribute__((address_space(3))) const bf16x8* lp;
;   p0 = f32x16{}; p1 = f32x16{};
; #pragma unroll
;   for (int d0 = 0; d0 < 12; ++d0) {
;     const int a = ka[d0 & 3] + (d0 >> 2) * 128 + BUFOFF;
;     const bf16x8 b0 = *(lp)(a), b1 = *(lp)(a + 12288);
;     bf16x8 qf;
;     qf = qr[d0];
;     p0 = __builtin_amdgcn_mfma_f32_32x32x16_bf16(b0, qf, p0, 0, 0, 0);
;     p1 = __builtin_amdgcn_mfma_f32_32x32x16_bf16(b1, qf, p1, 0, 0, 0);
;   }
; }
.LBB0_115:
	s_mov_b32 s55, s43
	s_mov_b32 s43, s52
	ds_read_b128 v[64:67], v169 offset:24576
	ds_read_b128 v[68:71], v169 offset:36864
	ds_read_b128 v[214:217], v190 offset:24576
	ds_read_b128 v[218:221], v190 offset:36864
	s_waitcnt lgkmcnt(0)
	v_mfma_f32_32x32x16_bf16 v[80:95], v[64:67], v[140:143], v[226:241]
	v_add_f32_e32 v144, v200, v145
	v_mfma_f32_32x32x16_bf16 v[64:79], v[68:71], v[140:143], v[226:241]
	v_add_f32_e32 v243, v203, v210
	v_add_f32_e32 v244, v202, v208
	v_add_f32_e32 v245, v205, v212
	v_add_f32_e32 v246, v199, v211
	v_add_f32_e32 v247, v201, v213
	v_mfma_f32_32x32x16_bf16 v[80:95], v[214:217], v[136:139], v[80:95]
	v_add_f32_e32 v251, v204, v207
	v_add_f32_e32 v252, v206, v209
	v_mov_b32_e32 v196, v158
	v_add_f32_e32 v144, v172, v144
	v_add_f32_e32 v243, v173, v243
	v_mfma_f32_32x32x16_bf16 v[64:79], v[218:221], v[136:139], v[64:79]
	ds_read_b128 v[214:217], v193 offset:24576
	ds_read_b128 v[218:221], v193 offset:36864
	v_add_f32_e32 v244, v170, v244
	v_add_f32_e32 v245, v171, v245
	v_add_f32_e32 v246, v196, v246
	v_mov_b32_e32 v222, v147
	v_mov_b32_e32 v223, v154
	v_mov_b32_e32 v224, v155
	s_waitcnt lgkmcnt(0)
	v_mfma_f32_32x32x16_bf16 v[80:95], v[214:217], v[132:135], v[80:95]
	v_mfma_f32_32x32x16_bf16 v[64:79], v[218:221], v[132:135], v[64:79]
	ds_read_b128 v[214:217], v192 offset:24576
	ds_read_b128 v[218:221], v192 offset:36864
	s_waitcnt lgkmcnt(0)
	v_mfma_f32_32x32x16_bf16 v[80:95], v[214:217], v[128:131], v[80:95]
	v_mfma_f32_32x32x16_bf16 v[64:79], v[218:221], v[128:131], v[64:79]
	ds_read_b128 v[214:217], v169 offset:24704
	ds_read_b128 v[218:221], v169 offset:36992
	s_waitcnt lgkmcnt(0)
	v_mfma_f32_32x32x16_bf16 v[80:95], v[214:217], v[124:127], v[80:95]
	v_mfma_f32_32x32x16_bf16 v[64:79], v[218:221], v[124:127], v[64:79]
	ds_read_b128 v[214:217], v190 offset:24704
	ds_read_b128 v[218:221], v190 offset:36992
	s_waitcnt lgkmcnt(0)
	v_mfma_f32_32x32x16_bf16 v[80:95], v[214:217], v[120:123], v[80:95]
	v_mfma_f32_32x32x16_bf16 v[64:79], v[218:221], v[120:123], v[64:79]
	ds_read_b128 v[214:217], v193 offset:24704
	ds_read_b128 v[218:221], v193 offset:36992
	s_waitcnt lgkmcnt(0)
	v_mfma_f32_32x32x16_bf16 v[80:95], v[214:217], v[116:119], v[80:95]
	v_mfma_f32_32x32x16_bf16 v[64:79], v[218:221], v[116:119], v[64:79]
	ds_read_b128 v[214:217], v192 offset:24704
	ds_read_b128 v[218:221], v192 offset:36992
	s_waitcnt lgkmcnt(0)
	v_mfma_f32_32x32x16_bf16 v[80:95], v[214:217], v[112:115], v[80:95]
	v_mfma_f32_32x32x16_bf16 v[64:79], v[218:221], v[112:115], v[64:79]
	ds_read_b128 v[214:217], v169 offset:24832
	ds_read_b128 v[218:221], v169 offset:37120
	s_waitcnt lgkmcnt(0)
	v_mfma_f32_32x32x16_bf16 v[80:95], v[214:217], v[108:111], v[80:95]
	v_mfma_f32_32x32x16_bf16 v[64:79], v[218:221], v[108:111], v[64:79]
	ds_read_b128 v[214:217], v190 offset:24832
	ds_read_b128 v[218:221], v190 offset:37120
	s_waitcnt lgkmcnt(0)
	v_mfma_f32_32x32x16_bf16 v[80:95], v[214:217], v[104:107], v[80:95]
	v_mfma_f32_32x32x16_bf16 v[64:79], v[218:221], v[104:107], v[64:79]
	ds_read_b128 v[214:217], v193 offset:24832
	ds_read_b128 v[218:221], v193 offset:37120
	s_waitcnt lgkmcnt(0)
	v_mfma_f32_32x32x16_bf16 v[80:95], v[214:217], v[100:103], v[80:95]
	v_mfma_f32_32x32x16_bf16 v[64:79], v[218:221], v[100:103], v[64:79]
	ds_read_b128 v[214:217], v192 offset:24832
	ds_read_b128 v[218:221], v192 offset:37120
	s_waitcnt lgkmcnt(0)
	v_mfma_f32_32x32x16_bf16 v[80:95], v[214:217], v[96:99], v[80:95]
	v_mov_b32_e32 v214, v159
	v_mov_b32_e32 v215, v152
	v_mov_b32_e32 v216, v153
	v_mov_b32_e32 v217, v150
	v_add_f32_e32 v247, v214, v247
	v_add_f32_e32 v251, v215, v251
	v_add_f32_e32 v252, v216, v252
	v_mfma_f32_32x32x16_bf16 v[64:79], v[218:221], v[96:99], v[64:79]
	v_mov_b32_e32 v218, v151
	v_mov_b32_e32 v219, v148
	v_mov_b32_e32 v220, v149
	v_mov_b32_e32 v221, v146
	v_add_f32_e32 v144, v217, v144
	v_add_f32_e32 v243, v218, v243
	v_add_f32_e32 v244, v219, v244
	v_add_f32_e32 v245, v220, v245
	v_add_f32_e32 v246, v221, v246
	v_add_f32_e32 v247, v222, v247
	v_add_f32_e32 v251, v223, v251
	v_add_f32_e32 v252, v224, v252
	v_add_f32_e32 v144, v144, v243
	v_add_f32_e32 v244, v244, v245
	v_add_f32_e32 v246, v246, v247
	v_add_f32_e32 v251, v251, v252
	v_add_f32_e32 v144, v144, v244
	v_add_f32_e32 v246, v246, v251
	v_add_f32_e32 v158, v144, v246
	v_mov_b32_e32 v159, v158
	v_cvt_pk_bf16_f32 v144, v145, v210
	v_cvt_pk_bf16_f32 v145, v208, v212
	v_cvt_pk_bf16_f32 v146, v211, v213
	v_cvt_pk_bf16_f32 v147, v207, v209
	v_cvt_pk_bf16_f32 v148, v200, v203
	v_cvt_pk_bf16_f32 v149, v202, v205
	v_cvt_pk_bf16_f32 v150, v199, v201
	v_cvt_pk_bf16_f32 v151, v204, v206
	v_cvt_pk_bf16_f32 v152, v172, v173
	v_cvt_pk_bf16_f32 v153, v170, v171
	v_cvt_pk_bf16_f32 v154, v196, v214
	s_nop 1
	v_permlane32_swap_b32_e32 v158, v159
	v_cvt_pk_bf16_f32 v155, v215, v216
	v_cvt_pk_bf16_f32 v170, v217, v218
	v_cvt_pk_bf16_f32 v171, v219, v220
	v_cvt_pk_bf16_f32 v172, v221, v222
	v_cvt_pk_bf16_f32 v173, v223, v224
	v_readlane_b32 s58, v249, 37
	v_readlane_b32 s59, v249, 38
	s_add_u32 s56, s58, s47
	s_addc_u32 s57, s59, s50
	s_add_u32 s4, s56, 0x17060000
	s_addc_u32 s5, s57, 0
	s_add_u32 s58, s58, s14
	s_addc_u32 s59, s59, s15
	s_add_u32 s60, s58, 0x1a040000
	s_mov_b32 m0, s41
	s_addc_u32 s61, s59, 0
	s_lshl_b32 s52, s54, 14
	s_add_i32 s62, s40, s52
	global_load_lds_dwordx4 v188, s[4:5]
	s_mov_b32 m0, s42
	s_nop 0
	global_load_lds_dwordx4 v189, s[4:5]
	s_add_i32 m0, s41, 0x4000
	s_nop 0
	global_load_lds_dwordx4 v191, s[4:5]
	s_mov_b32 m0, s62
	s_nop 0
	global_load_lds_dwordx4 v194, s[60:61]
	s_add_i32 m0, s62, 0x2000
	s_nop 0
	global_load_lds_dwordx4 v195, s[60:61]
	s_lshl_b32 s60, s43, 14
	v_add_u32_e32 v196, s60, v167
	ds_read_b64_tr_b16 v[200:201], v196 offset:0
	ds_read_b64_tr_b16 v[202:203], v196 offset:0x800
	ds_read_b64_tr_b16 v[204:205], v196 offset:0x1000
	ds_read_b64_tr_b16 v[206:207], v196 offset:0x1800
	ds_read_b64_tr_b16 v[208:209], v196 offset:0x2000
	ds_read_b64_tr_b16 v[210:211], v196 offset:0x2800
	ds_read_b64_tr_b16 v[212:213], v196 offset:0x3000
	ds_read_b64_tr_b16 v[214:215], v196 offset:0x3800
	s_nop 0
	s_waitcnt lgkmcnt(6)
; template <int MLA>
; __device__ __forceinline__ void partialSM(f32x16& p0, f32x16& p1, float& m_reg, float& mn, float& alpha) {
;     ...
;   float pmax = p0[0];
; #pragma unroll
;   for (int r = 1; r < 16; ++r) pmax = fmaxf(pmax, p0[r]);
; #pragma unroll
;   for (int r = 0; r < 16; ++r) pmax = fmaxf(pmax, p1[r]);
;   { auto rr = __builtin_amdgcn_permlane32_swap(__float_as_uint(pmax), __float_as_uint(pmax), false, false);
;     pmax = fmaxf(__uint_as_float(rr[0]), __uint_as_float(rr[1])); }
;   if (__builtin_expect(__all(pmax - m_reg <= THR / SCALE), 1)) { mn = m_reg; alpha = 1.f; }
;   else { mn = fmaxf(m_reg, pmax); alpha = __builtin_amdgcn_exp2f((m_reg - mn) * C); m_reg = mn; }
;   float mnC = -mn * C;
; #pragma unroll
;   for (int r = 0; r < 16; ++r) p0[r] = fmaf(p0[r], C, mnC);
; #pragma unroll
;   for (int r = 0; r < 16; ++r) p1[r] = fmaf(p1[r], C, mnC);
; #pragma unroll
;   for (int r = 0; r < 16; ++r) p0[r] = __builtin_amdgcn_exp2f(p0[r]);
; }
; __device__ __forceinline__ void finishSM(f32x16& p0, f32x16& p1, float alpha, float& l_reg, bf16x8& pa0, bf16x8& pa1, bf16x8& pa2, bf16x8& pa3) {
; #pragma unroll
;   for (int r = 0; r < 16; ++r) p1[r] = __builtin_amdgcn_exp2f(p1[r]);
;   float ps = 0;
; #pragma unroll
;   for (int r = 0; r < 16; ++r) ps += p0[r];
; #pragma unroll
;   for (int r = 0; r < 16; ++r) ps += p1[r];
;   { auto rr = __builtin_amdgcn_permlane32_swap(__float_as_uint(ps), __float_as_uint(ps), false, false);
;     ps = __uint_as_float(rr[0]) + __uint_as_float(rr[1]); }
;   l_reg = l_reg * alpha + ps;
; template <int D0> __device__ __forceinline__ void pv_one_t(f32x16& od, int vb, bf16x8 pa0, bf16x8 pa1, bf16x8 pa2, bf16x8 pa3) {
;   const s16x4 l0 = tr_read<v_rd_off(D0, 0, 0)>(vb), h0 = tr_read<v_rd_off(D0, 0, 1)>(vb), l1 = tr_read<v_rd_off(D0, 1, 0)>(vb), h1 = tr_read<v_rd_off(D0, 1, 1)>(vb);
;   const s16x4 l2 = tr_read<v_rd_off(D0, 2, 0)>(vb), h2 = tr_read<v_rd_off(D0, 2, 1)>(vb), l3 = tr_read<v_rd_off(D0, 3, 0)>(vb), h3 = tr_read<v_rd_off(D0, 3, 1)>(vb);
;   asm volatile("s_waitcnt lgkmcnt(0)" ::: "memory"); SBAR();
;     ...
;   od = __builtin_amdgcn_mfma_f32_32x32x16_bf16(PK(l0, h0), pa0, od, 0, 0, 0);
;   od = __builtin_amdgcn_mfma_f32_32x32x16_bf16(PK(l1, h1), pa1, od, 0, 0, 0);
;   od = __builtin_amdgcn_mfma_f32_32x32x16_bf16(PK(l2, h2), pa2, od, 0, 0, 0);
;   od = __builtin_amdgcn_mfma_f32_32x32x16_bf16(PK(l3, h3), pa3, od, 0, 0, 0);
;     ...
; }
	v_mfma_f32_32x32x16_bf16 v[0:15], v[200:203], v[144:147], v[0:15]
	ds_read_b64_tr_b16 v[200:201], v196 offset:0x200
	ds_read_b64_tr_b16 v[202:203], v196 offset:0xa00
	s_waitcnt lgkmcnt(6)
	v_mfma_f32_32x32x16_bf16 v[0:15], v[204:207], v[148:151], v[0:15]
	ds_read_b64_tr_b16 v[204:205], v196 offset:0x1200
	ds_read_b64_tr_b16 v[206:207], v196 offset:0x1a00
	s_waitcnt lgkmcnt(6)
	v_mfma_f32_32x32x16_bf16 v[0:15], v[208:211], v[152:155], v[0:15]
	ds_read_b64_tr_b16 v[208:209], v196 offset:0x2200
	ds_read_b64_tr_b16 v[210:211], v196 offset:0x2a00
	s_waitcnt lgkmcnt(6)
	v_mfma_f32_32x32x16_bf16 v[0:15], v[212:215], v[170:173], v[0:15]
	ds_read_b64_tr_b16 v[212:213], v196 offset:0x3200
	ds_read_b64_tr_b16 v[214:215], v196 offset:0x3a00
	s_waitcnt lgkmcnt(6)
	v_mfma_f32_32x32x16_bf16 v[48:63], v[200:203], v[144:147], v[48:63]
	ds_read_b64_tr_b16 v[200:201], v196 offset:0x400
	ds_read_b64_tr_b16 v[202:203], v196 offset:0xc00
	s_waitcnt lgkmcnt(6)
	v_mfma_f32_32x32x16_bf16 v[48:63], v[204:207], v[148:151], v[48:63]
	ds_read_b64_tr_b16 v[204:205], v196 offset:0x1400
	ds_read_b64_tr_b16 v[206:207], v196 offset:0x1c00
	s_waitcnt lgkmcnt(6)
	v_mfma_f32_32x32x16_bf16 v[48:63], v[208:211], v[152:155], v[48:63]
	ds_read_b64_tr_b16 v[208:209], v196 offset:0x2400
	ds_read_b64_tr_b16 v[210:211], v196 offset:0x2c00
	s_waitcnt lgkmcnt(6)
	v_mfma_f32_32x32x16_bf16 v[48:63], v[212:215], v[170:173], v[48:63]
	ds_read_b64_tr_b16 v[212:213], v196 offset:0x3400
	ds_read_b64_tr_b16 v[214:215], v196 offset:0x3c00
	s_waitcnt lgkmcnt(6)
	v_mfma_f32_32x32x16_bf16 v[32:47], v[200:203], v[144:147], v[32:47]
	ds_read_b64_tr_b16 v[200:201], v196 offset:0x600
	ds_read_b64_tr_b16 v[202:203], v196 offset:0xe00
	s_waitcnt lgkmcnt(6)
	v_mfma_f32_32x32x16_bf16 v[32:47], v[204:207], v[148:151], v[32:47]
	ds_read_b64_tr_b16 v[204:205], v196 offset:0x1600
	ds_read_b64_tr_b16 v[206:207], v196 offset:0x1e00
	s_waitcnt lgkmcnt(6)
	v_mfma_f32_32x32x16_bf16 v[32:47], v[208:211], v[152:155], v[32:47]
	ds_read_b64_tr_b16 v[208:209], v196 offset:0x2600
	ds_read_b64_tr_b16 v[210:211], v196 offset:0x2e00
	s_waitcnt lgkmcnt(6)
	v_mfma_f32_32x32x16_bf16 v[32:47], v[212:215], v[170:173], v[32:47]
	ds_read_b64_tr_b16 v[212:213], v196 offset:0x3600
	ds_read_b64_tr_b16 v[214:215], v196 offset:0x3e00
	s_waitcnt lgkmcnt(6)
	v_mfma_f32_32x32x16_bf16 v[16:31], v[200:203], v[144:147], v[16:31]
	v_max_f32_e32 v144, v80, v81
	v_max3_f32 v144, v144, v82, v83
	v_max3_f32 v144, v144, v84, v85
	v_max3_f32 v144, v144, v86, v87
	v_max3_f32 v144, v144, v88, v89
	v_max3_f32 v144, v144, v90, v91
	v_max3_f32 v144, v144, v92, v93
	s_waitcnt lgkmcnt(4)
	v_mfma_f32_32x32x16_bf16 v[16:31], v[204:207], v[148:151], v[16:31]
	v_max3_f32 v144, v144, v94, v95
	v_max3_f32 v144, v144, v64, v65
	v_max3_f32 v144, v144, v66, v67
	v_max3_f32 v144, v144, v68, v69
	v_max3_f32 v144, v144, v70, v71
	v_max3_f32 v144, v144, v72, v73
	v_max3_f32 v144, v144, v74, v75
	v_max3_f32 v144, v144, v76, v77
	s_waitcnt lgkmcnt(2)
	v_mfma_f32_32x32x16_bf16 v[16:31], v[208:211], v[152:155], v[16:31]
	v_max3_f32 v144, v144, v78, v79
	v_mov_b32_e32 v145, v144
	s_nop 1
	v_permlane32_swap_b32_e32 v144, v145
	v_max_f32_e32 v144, v144, v145
	v_cmp_nge_f32_e32 vcc, s63, v144
	s_waitcnt lgkmcnt(0)
	v_mfma_f32_32x32x16_bf16 v[16:31], v[212:215], v[170:173], v[16:31]
	s_waitcnt vmcnt(0) lgkmcnt(0)
	s_barrier
	s_cbranch_vccnz .Lrare_m1
	v_mov_b32_e32 v152, 1.0
.LBB0_117:
	v_exp_f32_e32 v155, v64
	v_exp_f32_e32 v170, v65
	v_exp_f32_e32 v171, v66
	v_exp_f32_e32 v172, v67
	v_exp_f32_e32 v173, v68
	v_exp_f32_e32 v197, v69
	v_exp_f32_e32 v199, v70
	v_exp_f32_e32 v200, v71
	v_exp_f32_e32 v201, v72
	v_exp_f32_e32 v202, v73
	v_exp_f32_e32 v203, v74
	v_exp_f32_e32 v204, v75
	v_exp_f32_e32 v205, v76
	v_exp_f32_e32 v222, v77
	v_exp_f32_e32 v223, v78
	v_exp_f32_e32 v154, v79
	v_exp_f32_e32 v206, v80
	v_exp_f32_e32 v207, v81
	v_exp_f32_e32 v208, v82
	v_exp_f32_e32 v209, v83
	v_exp_f32_e32 v210, v84
	v_exp_f32_e32 v211, v85
	v_exp_f32_e32 v212, v86
	v_exp_f32_e32 v213, v87
	v_exp_f32_e32 v214, v88
	v_exp_f32_e32 v215, v89
	v_exp_f32_e32 v216, v90
	v_exp_f32_e32 v217, v91
	v_exp_f32_e32 v218, v92
	v_exp_f32_e32 v219, v93
	v_exp_f32_e32 v220, v94
	v_exp_f32_e32 v221, v95
	ds_read_b128 v[64:67], v169
	ds_read_b128 v[68:71], v169 offset:12288
	ds_read_b128 v[144:147], v190
	ds_read_b128 v[148:151], v190 offset:12288
	v_mov_b32_e32 v224, v155
	s_waitcnt lgkmcnt(0)
	v_mfma_f32_32x32x16_bf16 v[80:95], v[64:67], v[140:143], v[226:241]
	v_mfma_f32_32x32x16_bf16 v[64:79], v[68:71], v[140:143], v[226:241]
	v_mov_b32_e32 v225, v154
	v_mfma_f32_32x32x16_bf16 v[80:95], v[144:147], v[136:139], v[80:95]
	v_mfma_f32_32x32x16_bf16 v[64:79], v[148:151], v[136:139], v[64:79]
	ds_read_b128 v[144:147], v193
	ds_read_b128 v[148:151], v193 offset:12288
	s_waitcnt lgkmcnt(0)
	v_mfma_f32_32x32x16_bf16 v[80:95], v[144:147], v[132:135], v[80:95]
	v_mfma_f32_32x32x16_bf16 v[64:79], v[148:151], v[132:135], v[64:79]
	ds_read_b128 v[144:147], v192
	ds_read_b128 v[148:151], v192 offset:12288
	s_waitcnt lgkmcnt(0)
	v_mfma_f32_32x32x16_bf16 v[80:95], v[144:147], v[128:131], v[80:95]
	v_mfma_f32_32x32x16_bf16 v[64:79], v[148:151], v[128:131], v[64:79]
	ds_read_b128 v[144:147], v169 offset:128
	ds_read_b128 v[148:151], v169 offset:12416
	s_waitcnt lgkmcnt(0)
	v_mfma_f32_32x32x16_bf16 v[80:95], v[144:147], v[124:127], v[80:95]
	v_mfma_f32_32x32x16_bf16 v[64:79], v[148:151], v[124:127], v[64:79]
	ds_read_b128 v[144:147], v190 offset:128
	ds_read_b128 v[148:151], v190 offset:12416
	s_waitcnt lgkmcnt(0)
; __device__ __forceinline__ void finishSM(f32x16& p0, f32x16& p1, float alpha, float& l_reg, bf16x8& pa0, bf16x8& pa1, bf16x8& pa2, bf16x8& pa3) {
; #pragma unroll
;   for (int r = 0; r < 16; ++r) p1[r] = __builtin_amdgcn_exp2f(p1[r]);
;   float ps = 0;
; #pragma unroll
;   for (int r = 0; r < 16; ++r) ps += p0[r];
; #pragma unroll
;   for (int r = 0; r < 16; ++r) ps += p1[r];
;   { auto rr = __builtin_amdgcn_permlane32_swap(__float_as_uint(ps), __float_as_uint(ps), false, false);
;     ps = __uint_as_float(rr[0]) + __uint_as_float(rr[1]); }
;   l_reg = l_reg * alpha + ps;
;     ...
;   PK4(p0, 0, pa0); PK4(p0, 8, pa1); PK4(p1, 0, pa2); PK4(p1, 8, pa3);
	v_mfma_f32_32x32x16_bf16 v[80:95], v[144:147], v[120:123], v[80:95]
	v_mfma_f32_32x32x16_bf16 v[64:79], v[148:151], v[120:123], v[64:79]
	ds_read_b128 v[144:147], v193 offset:128
	ds_read_b128 v[148:151], v193 offset:12416
	s_waitcnt lgkmcnt(0)
	v_mfma_f32_32x32x16_bf16 v[80:95], v[144:147], v[116:119], v[80:95]
	v_mfma_f32_32x32x16_bf16 v[64:79], v[148:151], v[116:119], v[64:79]
	ds_read_b128 v[144:147], v192 offset:128
	ds_read_b128 v[148:151], v192 offset:12416
	s_waitcnt lgkmcnt(0)
	v_mfma_f32_32x32x16_bf16 v[80:95], v[144:147], v[112:115], v[80:95]
	v_mfma_f32_32x32x16_bf16 v[64:79], v[148:151], v[112:115], v[64:79]
	ds_read_b128 v[144:147], v169 offset:256
	ds_read_b128 v[148:151], v169 offset:12544
	s_waitcnt lgkmcnt(0)
	v_mfma_f32_32x32x16_bf16 v[80:95], v[144:147], v[108:111], v[80:95]
	v_mfma_f32_32x32x16_bf16 v[64:79], v[148:151], v[108:111], v[64:79]
	ds_read_b128 v[144:147], v190 offset:256
	ds_read_b128 v[148:151], v190 offset:12544
	s_waitcnt lgkmcnt(0)
	v_mfma_f32_32x32x16_bf16 v[80:95], v[144:147], v[104:107], v[80:95]
	v_mfma_f32_32x32x16_bf16 v[64:79], v[148:151], v[104:107], v[64:79]
	ds_read_b128 v[144:147], v193 offset:256
	ds_read_b128 v[148:151], v193 offset:12544
	s_waitcnt lgkmcnt(0)
	v_mfma_f32_32x32x16_bf16 v[80:95], v[144:147], v[100:103], v[80:95]
	v_mfma_f32_32x32x16_bf16 v[64:79], v[148:151], v[100:103], v[64:79]
	ds_read_b128 v[144:147], v192 offset:256
	ds_read_b128 v[148:151], v192 offset:12544
	s_waitcnt lgkmcnt(0)
	v_mfma_f32_32x32x16_bf16 v[80:95], v[144:147], v[96:99], v[80:95]
	v_add_f32_e32 v144, v214, v206
	v_add_f32_e32 v243, v215, v207
	v_add_f32_e32 v244, v216, v208
	v_add_f32_e32 v245, v217, v209
	v_add_f32_e32 v246, v218, v210
	v_add_f32_e32 v247, v219, v211
	v_add_f32_e32 v251, v220, v212
	v_add_f32_e32 v252, v221, v213
	v_add_f32_e32 v144, v224, v144
	v_add_f32_e32 v243, v170, v243
	v_add_f32_e32 v244, v171, v244
	v_add_f32_e32 v245, v172, v245
	v_add_f32_e32 v246, v173, v246
	v_add_f32_e32 v247, v197, v247
	v_add_f32_e32 v251, v199, v251
	v_add_f32_e32 v252, v200, v252
	v_add_f32_e32 v144, v201, v144
	v_add_f32_e32 v243, v202, v243
	v_mfma_f32_32x32x16_bf16 v[64:79], v[148:151], v[96:99], v[64:79]
	v_add_f32_e32 v244, v203, v244
	v_add_f32_e32 v245, v204, v245
	v_add_f32_e32 v246, v205, v246
	v_add_f32_e32 v247, v222, v247
	v_add_f32_e32 v251, v223, v251
	v_add_f32_e32 v252, v225, v252
	v_add_f32_e32 v144, v144, v243
	v_add_f32_e32 v244, v244, v245
	v_add_f32_e32 v246, v246, v247
	v_add_f32_e32 v251, v251, v252
	v_add_f32_e32 v144, v144, v244
	v_add_f32_e32 v246, v246, v251
	v_add_f32_e32 v154, v144, v246
	v_mov_b32_e32 v155, v154
	v_cvt_pk_bf16_f32 v144, v206, v207
	v_cvt_pk_bf16_f32 v145, v208, v209
	v_cvt_pk_bf16_f32 v146, v210, v211
	v_cvt_pk_bf16_f32 v147, v212, v213
	s_nop 1
	v_permlane32_swap_b32_e32 v154, v155
	v_cvt_pk_bf16_f32 v148, v214, v215
	v_cvt_pk_bf16_f32 v149, v216, v217
	v_cvt_pk_bf16_f32 v150, v218, v219
	v_cvt_pk_bf16_f32 v151, v220, v221
	v_cvt_pk_bf16_f32 v170, v224, v170
	v_cvt_pk_bf16_f32 v171, v171, v172
	v_cvt_pk_bf16_f32 v172, v173, v197
	v_cvt_pk_bf16_f32 v173, v199, v200
	v_cvt_pk_bf16_f32 v200, v201, v202
	v_cvt_pk_bf16_f32 v201, v203, v204
	v_cvt_pk_bf16_f32 v202, v205, v222
	v_cvt_pk_bf16_f32 v203, v223, v225
	s_nop 0
	s_add_u32 s4, s56, 0x17090000
	s_addc_u32 s5, s57, 0
	s_add_u32 s56, s58, 0x1a060000
	s_mov_b32 m0, s16
	s_addc_u32 s57, s59, 0
	s_add_i32 s58, s40, s60
	global_load_lds_dwordx4 v188, s[4:5]
	s_mov_b32 m0, s17
	s_nop 0
	global_load_lds_dwordx4 v189, s[4:5]
	s_mov_b32 m0, s44
	s_nop 0
	global_load_lds_dwordx4 v191, s[4:5]
	s_mov_b32 m0, s58
	s_nop 0
	global_load_lds_dwordx4 v194, s[56:57]
	s_add_i32 m0, s58, 0x2000
	s_nop 0
	global_load_lds_dwordx4 v195, s[56:57]
	v_lshl_add_u32 v197, s55, 14, v167
	ds_read_b64_tr_b16 v[204:205], v197 offset:0
	ds_read_b64_tr_b16 v[206:207], v197 offset:0x800
	ds_read_b64_tr_b16 v[208:209], v197 offset:0x1000
	ds_read_b64_tr_b16 v[210:211], v197 offset:0x1800
	ds_read_b64_tr_b16 v[212:213], v197 offset:0x2000
	ds_read_b64_tr_b16 v[214:215], v197 offset:0x2800
	ds_read_b64_tr_b16 v[216:217], v197 offset:0x3000
	ds_read_b64_tr_b16 v[218:219], v197 offset:0x3800
	s_nop 0
	s_waitcnt lgkmcnt(6)
; #define SBAR() __builtin_amdgcn_sched_barrier(0)
; template <int MLA>
; __device__ __forceinline__ void partialSM(f32x16& p0, f32x16& p1, float& m_reg, float& mn, float& alpha) {
;     ...
;   float pmax = p0[0];
; #pragma unroll
;   for (int r = 1; r < 16; ++r) pmax = fmaxf(pmax, p0[r]);
; #pragma unroll
;   for (int r = 0; r < 16; ++r) pmax = fmaxf(pmax, p1[r]);
;   { auto rr = __builtin_amdgcn_permlane32_swap(__float_as_uint(pmax), __float_as_uint(pmax), false, false);
;     pmax = fmaxf(__uint_as_float(rr[0]), __uint_as_float(rr[1])); }
;   if (__builtin_expect(__all(pmax - m_reg <= THR / SCALE), 1)) { mn = m_reg; alpha = 1.f; }
;   else { mn = fmaxf(m_reg, pmax); alpha = __builtin_amdgcn_exp2f((m_reg - mn) * C); m_reg = mn; }
; template <int D0> __device__ __forceinline__ void pv_one_t(f32x16& od, int vb, bf16x8 pa0, bf16x8 pa1, bf16x8 pa2, bf16x8 pa3) {
;   const s16x4 l0 = tr_read<v_rd_off(D0, 0, 0)>(vb), h0 = tr_read<v_rd_off(D0, 0, 1)>(vb), l1 = tr_read<v_rd_off(D0, 1, 0)>(vb), h1 = tr_read<v_rd_off(D0, 1, 1)>(vb);
;   const s16x4 l2 = tr_read<v_rd_off(D0, 2, 0)>(vb), h2 = tr_read<v_rd_off(D0, 2, 1)>(vb), l3 = tr_read<v_rd_off(D0, 3, 0)>(vb), h3 = tr_read<v_rd_off(D0, 3, 1)>(vb);
;   asm volatile("s_waitcnt lgkmcnt(0)" ::: "memory"); SBAR();
;     ...
;   od = __builtin_amdgcn_mfma_f32_32x32x16_bf16(PK(l0, h0), pa0, od, 0, 0, 0);
;   od = __builtin_amdgcn_mfma_f32_32x32x16_bf16(PK(l1, h1), pa1, od, 0, 0, 0);
;   od = __builtin_amdgcn_mfma_f32_32x32x16_bf16(PK(l2, h2), pa2, od, 0, 0, 0);
;   od = __builtin_amdgcn_mfma_f32_32x32x16_bf16(PK(l3, h3), pa3, od, 0, 0, 0);
;     ...
; }
	v_mfma_f32_32x32x16_bf16 v[0:15], v[204:207], v[144:147], v[0:15]
	ds_read_b64_tr_b16 v[204:205], v197 offset:0x200
	ds_read_b64_tr_b16 v[206:207], v197 offset:0xa00
	s_waitcnt lgkmcnt(6)
	v_mfma_f32_32x32x16_bf16 v[0:15], v[208:211], v[148:151], v[0:15]
	ds_read_b64_tr_b16 v[208:209], v197 offset:0x1200
	ds_read_b64_tr_b16 v[210:211], v197 offset:0x1a00
	s_waitcnt lgkmcnt(6)
	v_mfma_f32_32x32x16_bf16 v[0:15], v[212:215], v[170:173], v[0:15]
	ds_read_b64_tr_b16 v[212:213], v197 offset:0x2200
	ds_read_b64_tr_b16 v[214:215], v197 offset:0x2a00
	s_waitcnt lgkmcnt(6)
	v_mfma_f32_32x32x16_bf16 v[0:15], v[216:219], v[200:203], v[0:15]
	ds_read_b64_tr_b16 v[216:217], v197 offset:0x3200
	ds_read_b64_tr_b16 v[218:219], v197 offset:0x3a00
	s_waitcnt lgkmcnt(6)
	v_mfma_f32_32x32x16_bf16 v[48:63], v[204:207], v[144:147], v[48:63]
	ds_read_b64_tr_b16 v[204:205], v197 offset:0x400
	ds_read_b64_tr_b16 v[206:207], v197 offset:0xc00
	s_waitcnt lgkmcnt(6)
	v_mfma_f32_32x32x16_bf16 v[48:63], v[208:211], v[148:151], v[48:63]
	ds_read_b64_tr_b16 v[208:209], v197 offset:0x1400
	ds_read_b64_tr_b16 v[210:211], v197 offset:0x1c00
	s_waitcnt lgkmcnt(6)
	v_mfma_f32_32x32x16_bf16 v[48:63], v[212:215], v[170:173], v[48:63]
	ds_read_b64_tr_b16 v[212:213], v197 offset:0x2400
	ds_read_b64_tr_b16 v[214:215], v197 offset:0x2c00
	s_waitcnt lgkmcnt(6)
	v_mfma_f32_32x32x16_bf16 v[48:63], v[216:219], v[200:203], v[48:63]
	ds_read_b64_tr_b16 v[216:217], v197 offset:0x3400
	ds_read_b64_tr_b16 v[218:219], v197 offset:0x3c00
	s_waitcnt lgkmcnt(6)
	v_mfma_f32_32x32x16_bf16 v[32:47], v[204:207], v[144:147], v[32:47]
	ds_read_b64_tr_b16 v[204:205], v197 offset:0x600
	ds_read_b64_tr_b16 v[206:207], v197 offset:0xe00
	s_waitcnt lgkmcnt(6)
	v_mfma_f32_32x32x16_bf16 v[32:47], v[208:211], v[148:151], v[32:47]
	ds_read_b64_tr_b16 v[208:209], v197 offset:0x1600
	ds_read_b64_tr_b16 v[210:211], v197 offset:0x1e00
	s_waitcnt lgkmcnt(6)
	v_mfma_f32_32x32x16_bf16 v[32:47], v[212:215], v[170:173], v[32:47]
	ds_read_b64_tr_b16 v[212:213], v197 offset:0x2600
	ds_read_b64_tr_b16 v[214:215], v197 offset:0x2e00
	s_waitcnt lgkmcnt(6)
	v_mfma_f32_32x32x16_bf16 v[32:47], v[216:219], v[200:203], v[32:47]
	ds_read_b64_tr_b16 v[216:217], v197 offset:0x3600
	ds_read_b64_tr_b16 v[218:219], v197 offset:0x3e00
	s_waitcnt lgkmcnt(6)
	v_mfma_f32_32x32x16_bf16 v[16:31], v[204:207], v[144:147], v[16:31]
	v_max_f32_e32 v144, v80, v81
	v_max3_f32 v144, v144, v82, v83
	v_max3_f32 v144, v144, v84, v85
	v_max3_f32 v144, v144, v86, v87
	v_max3_f32 v144, v144, v88, v89
	v_max3_f32 v144, v144, v90, v91
	v_max3_f32 v144, v144, v92, v93
	s_waitcnt lgkmcnt(4)
	v_mfma_f32_32x32x16_bf16 v[16:31], v[208:211], v[148:151], v[16:31]
	v_max3_f32 v144, v144, v94, v95
	v_max3_f32 v144, v144, v64, v65
	v_max3_f32 v144, v144, v66, v67
	v_max3_f32 v144, v144, v68, v69
	v_max3_f32 v144, v144, v70, v71
	v_max3_f32 v144, v144, v72, v73
	v_max3_f32 v144, v144, v74, v75
	v_max3_f32 v144, v144, v76, v77
	s_waitcnt lgkmcnt(2)
	v_mfma_f32_32x32x16_bf16 v[16:31], v[212:215], v[170:173], v[16:31]
	v_max3_f32 v144, v144, v78, v79
	v_mov_b32_e32 v145, v144
	s_nop 1
	v_permlane32_swap_b32_e32 v144, v145
	v_max_f32_e32 v144, v144, v145
	v_cmp_nge_f32_e32 vcc, s63, v144
	s_waitcnt lgkmcnt(0)
	v_mfma_f32_32x32x16_bf16 v[16:31], v[216:219], v[200:203], v[16:31]
	s_waitcnt vmcnt(0) lgkmcnt(0)
	s_barrier
	s_cbranch_vccnz .Lrare_m2
	v_mov_b32_e32 v144, 1.0

; __device__ __forceinline__ void finishSM(f32x16& p0, f32x16& p1, float alpha, float& l_reg, bf16x8& pa0, bf16x8& pa1, bf16x8& pa2, bf16x8& pa3) {
; #pragma unroll
;   for (int r = 0; r < 16; ++r) p1[r] = __builtin_amdgcn_exp2f(p1[r]);
;   float ps = 0;
; #pragma unroll
;   for (int r = 0; r < 16; ++r) ps += p0[r];
; #pragma unroll
;   for (int r = 0; r < 16; ++r) ps += p1[r];
;   { auto rr = __builtin_amdgcn_permlane32_swap(__float_as_uint(ps), __float_as_uint(ps), false, false);
;     ps = __uint_as_float(rr[0]) + __uint_as_float(rr[1]); }
;   l_reg = l_reg * alpha + ps;
;     ...
;   PK4(p0, 0, pa0); PK4(p0, 8, pa1); PK4(p1, 0, pa2); PK4(p1, 8, pa3);
; template <int BUFOFF>
; __device__ __forceinline__ void qkt_diff(f32x16& p0, f32x16& p1, const int* ka, const bf16x8* qr) {
;   typedef __attribute__((address_space(3))) const bf16x8* lp;
;   p0 = f32x16{}; p1 = f32x16{};
; #pragma unroll
;   for (int d0 = 0; d0 < 4; ++d0) {
;     const int a = ka[d0] + BUFOFF;
;     const bf16x8 b0 = *(lp)(a), b1 = *(lp)(a + 8192);
;     p0 = __builtin_amdgcn_mfma_f32_32x32x16_bf16(b0, qr[d0], p0, 0, 0, 0);
;     p1 = __builtin_amdgcn_mfma_f32_32x32x16_bf16(b1, qr[d0], p1, 0, 0, 0);
;   }
; }
.LBB0_129:
	s_mov_b32 s54, s47
	s_mov_b32 s47, s52
	ds_read_b128 v[64:67], v138 offset:16384
	ds_read_b128 v[68:71], v138 offset:24576
	ds_read_b128 v[170:173], v141 offset:16384
	ds_read_b128 v[188:191], v141 offset:24576
	s_waitcnt lgkmcnt(0)
	v_mfma_f32_32x32x16_bf16 v[80:95], v[64:67], v[108:111], v[226:241]
	v_add_f32_e32 v112, v144, v113
	v_mfma_f32_32x32x16_bf16 v[64:79], v[68:71], v[108:111], v[226:241]
	v_add_f32_e32 v243, v148, v155
	v_add_f32_e32 v244, v145, v152
	v_add_f32_e32 v245, v149, v156
	v_add_f32_e32 v246, v146, v153
	v_add_f32_e32 v247, v150, v158
	v_mfma_f32_32x32x16_bf16 v[80:95], v[170:173], v[104:107], v[80:95]
	v_add_f32_e32 v251, v147, v154
	v_add_f32_e32 v252, v151, v159
	v_mov_b32_e32 v132, v124
	v_add_f32_e32 v112, v128, v112
	v_mov_b32_e32 v162, v125
	v_mfma_f32_32x32x16_bf16 v[64:79], v[188:191], v[104:107], v[64:79]
	ds_read_b128 v[170:173], v140 offset:16384
	ds_read_b128 v[188:191], v140 offset:24576
	v_add_f32_e32 v243, v129, v243
	v_mov_b32_e32 v167, v120
	v_add_f32_e32 v244, v126, v244
	v_mov_b32_e32 v169, v121
	v_add_f32_e32 v245, v127, v245
	v_add_f32_e32 v246, v132, v246
	s_waitcnt lgkmcnt(0)
	v_mfma_f32_32x32x16_bf16 v[80:95], v[170:173], v[100:103], v[80:95]
	v_add_f32_e32 v247, v162, v247
	v_add_f32_e32 v251, v167, v251
	v_add_f32_e32 v252, v169, v252
	v_mfma_f32_32x32x16_bf16 v[64:79], v[188:191], v[100:103], v[64:79]
	ds_read_b128 v[170:173], v139 offset:16384
	ds_read_b128 v[188:191], v139 offset:24576
	s_waitcnt lgkmcnt(0)
	v_mfma_f32_32x32x16_bf16 v[80:95], v[170:173], v[96:99], v[80:95]
	v_mov_b32_e32 v170, v118
	v_mov_b32_e32 v171, v117
	v_mov_b32_e32 v172, v114
	v_mov_b32_e32 v173, v115
	v_add_f32_e32 v112, v170, v112
	v_add_f32_e32 v243, v119, v243
	v_add_f32_e32 v244, v116, v244
	v_mfma_f32_32x32x16_bf16 v[64:79], v[188:191], v[96:99], v[64:79]
	v_mov_b32_e32 v188, v122
	v_mov_b32_e32 v189, v123
	v_add_f32_e32 v245, v171, v245
	v_add_f32_e32 v246, v172, v246
	v_add_f32_e32 v247, v173, v247
	v_add_f32_e32 v251, v188, v251
	v_add_f32_e32 v252, v189, v252
	v_add_f32_e32 v112, v112, v243
	v_add_f32_e32 v244, v244, v245
	v_add_f32_e32 v246, v246, v247
	v_add_f32_e32 v251, v251, v252
	v_add_f32_e32 v112, v112, v244
	v_add_f32_e32 v246, v246, v251
	v_add_f32_e32 v117, v112, v246
	v_mov_b32_e32 v118, v117
	v_cvt_pk_bf16_f32 v112, v113, v155
	v_cvt_pk_bf16_f32 v113, v152, v156
	v_cvt_pk_bf16_f32 v114, v153, v158
	s_nop 1
	v_permlane32_swap_b32_e32 v117, v118
	v_cvt_pk_bf16_f32 v115, v154, v159
	v_cvt_pk_bf16_f32 v120, v144, v148
	v_cvt_pk_bf16_f32 v121, v145, v149
	v_cvt_pk_bf16_f32 v122, v146, v150
	v_cvt_pk_bf16_f32 v123, v147, v151
	v_cvt_pk_bf16_f32 v124, v128, v129
	v_cvt_pk_bf16_f32 v125, v126, v127
	v_cvt_pk_bf16_f32 v126, v132, v162
	v_cvt_pk_bf16_f32 v127, v167, v169
	v_cvt_pk_bf16_f32 v144, v170, v119
	v_cvt_pk_bf16_f32 v145, v116, v171
	v_cvt_pk_bf16_f32 v146, v172, v173
	v_cvt_pk_bf16_f32 v147, v188, v189
	s_add_u32 s4, s14, 0x2000000
	s_mov_b32 m0, s43
	s_addc_u32 s5, s15, 0
	s_mov_b64 s[56:57], s[14:15]
	s_lshl_b32 s52, s53, 14
	s_add_i32 s55, s42, s52
	s_nop 0
	global_load_lds_dwordx4 v134, s[56:57]
	s_mov_b32 m0, s44
	s_nop 0
	global_load_lds_dwordx4 v135, s[56:57]
	s_mov_b32 m0, s55
	s_nop 0
	global_load_lds_dwordx4 v136, s[4:5]
	s_add_i32 m0, s55, 0x2000
	s_nop 0
	global_load_lds_dwordx4 v137, s[4:5]
	s_lshl_b32 s55, s47, 14
	v_add_u32_e32 v132, s55, v133
	ds_read_b64_tr_b16 v[148:149], v132 offset:0
	ds_read_b64_tr_b16 v[150:151], v132 offset:0x800
	ds_read_b64_tr_b16 v[152:153], v132 offset:0x1000
	ds_read_b64_tr_b16 v[154:155], v132 offset:0x1800
	ds_read_b64_tr_b16 v[170:171], v132 offset:0x2000
	ds_read_b64_tr_b16 v[172:173], v132 offset:0x2800
	ds_read_b64_tr_b16 v[188:189], v132 offset:0x3000
	ds_read_b64_tr_b16 v[190:191], v132 offset:0x3800
	s_nop 0
	s_waitcnt lgkmcnt(6)
	v_mfma_f32_32x32x16_bf16 v[32:47], v[148:151], v[112:115], v[32:47]
	ds_read_b64_tr_b16 v[148:149], v132 offset:0x200
	ds_read_b64_tr_b16 v[150:151], v132 offset:0xa00
	s_waitcnt lgkmcnt(6)
	v_mfma_f32_32x32x16_bf16 v[32:47], v[152:155], v[120:123], v[32:47]
	ds_read_b64_tr_b16 v[152:153], v132 offset:0x1200
	ds_read_b64_tr_b16 v[154:155], v132 offset:0x1a00
	s_waitcnt lgkmcnt(6)
	v_mfma_f32_32x32x16_bf16 v[32:47], v[170:173], v[124:127], v[32:47]
	ds_read_b64_tr_b16 v[170:171], v132 offset:0x2200
	ds_read_b64_tr_b16 v[172:173], v132 offset:0x2a00
	s_waitcnt lgkmcnt(6)
	v_mfma_f32_32x32x16_bf16 v[32:47], v[188:191], v[144:147], v[32:47]
	ds_read_b64_tr_b16 v[188:189], v132 offset:0x3200
	ds_read_b64_tr_b16 v[190:191], v132 offset:0x3a00
	s_waitcnt lgkmcnt(6)
	v_mfma_f32_32x32x16_bf16 v[48:63], v[148:151], v[112:115], v[48:63]
	ds_read_b64_tr_b16 v[148:149], v132 offset:0x400
	ds_read_b64_tr_b16 v[150:151], v132 offset:0xc00
	s_waitcnt lgkmcnt(6)
	v_mfma_f32_32x32x16_bf16 v[48:63], v[152:155], v[120:123], v[48:63]
	ds_read_b64_tr_b16 v[152:153], v132 offset:0x1400
	ds_read_b64_tr_b16 v[154:155], v132 offset:0x1c00
	s_waitcnt lgkmcnt(6)
	v_mfma_f32_32x32x16_bf16 v[48:63], v[170:173], v[124:127], v[48:63]
	ds_read_b64_tr_b16 v[170:171], v132 offset:0x2400
	ds_read_b64_tr_b16 v[172:173], v132 offset:0x2c00
	s_waitcnt lgkmcnt(6)
	v_mfma_f32_32x32x16_bf16 v[48:63], v[188:191], v[144:147], v[48:63]
	ds_read_b64_tr_b16 v[188:189], v132 offset:0x3400
	ds_read_b64_tr_b16 v[190:191], v132 offset:0x3c00
	s_waitcnt lgkmcnt(6)
	v_mfma_f32_32x32x16_bf16 v[16:31], v[148:151], v[112:115], v[16:31]
	ds_read_b64_tr_b16 v[148:149], v132 offset:0x600
	ds_read_b64_tr_b16 v[150:151], v132 offset:0xe00
	s_waitcnt lgkmcnt(6)
	v_mfma_f32_32x32x16_bf16 v[16:31], v[152:155], v[120:123], v[16:31]
	ds_read_b64_tr_b16 v[152:153], v132 offset:0x1600
	ds_read_b64_tr_b16 v[154:155], v132 offset:0x1e00
	s_waitcnt lgkmcnt(6)
; template <int MLA>
; __device__ __forceinline__ void partialSM(f32x16& p0, f32x16& p1, float& m_reg, float& mn, float& alpha) {
;     ...
;   float pmax = p0[0];
; #pragma unroll
;   for (int r = 1; r < 16; ++r) pmax = fmaxf(pmax, p0[r]);
; #pragma unroll
;   for (int r = 0; r < 16; ++r) pmax = fmaxf(pmax, p1[r]);
;   { auto rr = __builtin_amdgcn_permlane32_swap(__float_as_uint(pmax), __float_as_uint(pmax), false, false);
;     pmax = fmaxf(__uint_as_float(rr[0]), __uint_as_float(rr[1])); }
;   if (__builtin_expect(__all(pmax - m_reg <= THR / SCALE), 1)) { mn = m_reg; alpha = 1.f; }
;   else { mn = fmaxf(m_reg, pmax); alpha = __builtin_amdgcn_exp2f((m_reg - mn) * C); m_reg = mn; }
;   float mnC = -mn * C;
; #pragma unroll
;   for (int r = 0; r < 16; ++r) p0[r] = fmaf(p0[r], C, mnC);
; #pragma unroll
;   for (int r = 0; r < 16; ++r) p1[r] = fmaf(p1[r], C, mnC);
; #pragma unroll
;   for (int r = 0; r < 16; ++r) p0[r] = __builtin_amdgcn_exp2f(p0[r]);
; }
; __device__ __forceinline__ void finishSM(f32x16& p0, f32x16& p1, float alpha, float& l_reg, bf16x8& pa0, bf16x8& pa1, bf16x8& pa2, bf16x8& pa3) {
; #pragma unroll
;   for (int r = 0; r < 16; ++r) p1[r] = __builtin_amdgcn_exp2f(p1[r]);
;   float ps = 0;
; #pragma unroll
;   for (int r = 0; r < 16; ++r) ps += p0[r];
; #pragma unroll
;   for (int r = 0; r < 16; ++r) ps += p1[r];
;   { auto rr = __builtin_amdgcn_permlane32_swap(__float_as_uint(ps), __float_as_uint(ps), false, false);
;     ps = __uint_as_float(rr[0]) + __uint_as_float(rr[1]); }
;   l_reg = l_reg * alpha + ps;
; template <int D0> __device__ __forceinline__ void pv_one_t(f32x16& od, int vb, bf16x8 pa0, bf16x8 pa1, bf16x8 pa2, bf16x8 pa3) {
;   const s16x4 l0 = tr_read<v_rd_off(D0, 0, 0)>(vb), h0 = tr_read<v_rd_off(D0, 0, 1)>(vb), l1 = tr_read<v_rd_off(D0, 1, 0)>(vb), h1 = tr_read<v_rd_off(D0, 1, 1)>(vb);
;   const s16x4 l2 = tr_read<v_rd_off(D0, 2, 0)>(vb), h2 = tr_read<v_rd_off(D0, 2, 1)>(vb), l3 = tr_read<v_rd_off(D0, 3, 0)>(vb), h3 = tr_read<v_rd_off(D0, 3, 1)>(vb);
;   asm volatile("s_waitcnt lgkmcnt(0)" ::: "memory"); SBAR();
;     ...
;   od = __builtin_amdgcn_mfma_f32_32x32x16_bf16(PK(l0, h0), pa0, od, 0, 0, 0);
;   od = __builtin_amdgcn_mfma_f32_32x32x16_bf16(PK(l1, h1), pa1, od, 0, 0, 0);
;   od = __builtin_amdgcn_mfma_f32_32x32x16_bf16(PK(l2, h2), pa2, od, 0, 0, 0);
;   od = __builtin_amdgcn_mfma_f32_32x32x16_bf16(PK(l3, h3), pa3, od, 0, 0, 0);
;     ...
; }
	v_mfma_f32_32x32x16_bf16 v[16:31], v[170:173], v[124:127], v[16:31]
	ds_read_b64_tr_b16 v[170:171], v132 offset:0x2600
	ds_read_b64_tr_b16 v[172:173], v132 offset:0x2e00
	s_waitcnt lgkmcnt(6)
	v_mfma_f32_32x32x16_bf16 v[16:31], v[188:191], v[144:147], v[16:31]
	ds_read_b64_tr_b16 v[188:189], v132 offset:0x3600
	ds_read_b64_tr_b16 v[190:191], v132 offset:0x3e00
	s_waitcnt lgkmcnt(6)
	v_mfma_f32_32x32x16_bf16 v[0:15], v[148:151], v[112:115], v[0:15]
	v_max_f32_e32 v112, v80, v81
	v_max3_f32 v112, v112, v82, v83
	v_max3_f32 v112, v112, v84, v85
	v_max3_f32 v112, v112, v86, v87
	v_max3_f32 v112, v112, v88, v89
	v_max3_f32 v112, v112, v90, v91
	v_max3_f32 v112, v112, v92, v93
	s_waitcnt lgkmcnt(4)
	v_mfma_f32_32x32x16_bf16 v[0:15], v[152:155], v[120:123], v[0:15]
	v_max3_f32 v112, v112, v94, v95
	v_max3_f32 v112, v112, v64, v65
	v_max3_f32 v112, v112, v66, v67
	v_max3_f32 v112, v112, v68, v69
	v_max3_f32 v112, v112, v70, v71
	v_max3_f32 v112, v112, v72, v73
	v_max3_f32 v112, v112, v74, v75
	v_max3_f32 v112, v112, v76, v77
	s_waitcnt lgkmcnt(2)
	v_mfma_f32_32x32x16_bf16 v[0:15], v[170:173], v[124:127], v[0:15]
	v_max3_f32 v112, v112, v78, v79
	v_mov_b32_e32 v113, v112
	s_nop 1
	v_permlane32_swap_b32_e32 v112, v113
	v_max_f32_e32 v112, v112, v113
	v_cmp_nge_f32_e32 vcc, s70, v112
	s_waitcnt lgkmcnt(0)
	v_mfma_f32_32x32x16_bf16 v[0:15], v[188:191], v[144:147], v[0:15]
	s_waitcnt vmcnt(0) lgkmcnt(0)
	s_barrier
	s_cbranch_vccnz .Lrare_d1
	v_mov_b32_e32 v116, 1.0
.LBB0_131:
	v_exp_f32_e32 v125, v64
	v_exp_f32_e32 v126, v65
	v_exp_f32_e32 v127, v66
	v_exp_f32_e32 v128, v67
	v_exp_f32_e32 v129, v68
	v_exp_f32_e32 v143, v69
	v_exp_f32_e32 v144, v70
	v_exp_f32_e32 v145, v71
	v_exp_f32_e32 v146, v72
	v_exp_f32_e32 v147, v73
	v_exp_f32_e32 v148, v74
	v_exp_f32_e32 v149, v75
	v_exp_f32_e32 v150, v76
	v_exp_f32_e32 v151, v80
	v_exp_f32_e32 v152, v81
	v_exp_f32_e32 v153, v82
	v_exp_f32_e32 v154, v83
	v_exp_f32_e32 v155, v84
	v_exp_f32_e32 v156, v85
	v_exp_f32_e32 v158, v86
	v_exp_f32_e32 v159, v87
	v_exp_f32_e32 v162, v88
	v_exp_f32_e32 v167, v89
	v_exp_f32_e32 v169, v90
	v_exp_f32_e32 v170, v91
	v_exp_f32_e32 v171, v92
	v_exp_f32_e32 v172, v93
	v_exp_f32_e32 v173, v94
	v_exp_f32_e32 v188, v95
	v_exp_f32_e32 v189, v77
	v_exp_f32_e32 v190, v78
	v_exp_f32_e32 v124, v79
	ds_read_b128 v[64:67], v138
	ds_read_b128 v[68:71], v138 offset:8192
	ds_read_b128 v[112:115], v141
	ds_read_b128 v[120:123], v141 offset:8192
	v_mov_b32_e32 v191, v125
	s_waitcnt lgkmcnt(0)
	v_mfma_f32_32x32x16_bf16 v[80:95], v[64:67], v[108:111], v[226:241]
	v_mfma_f32_32x32x16_bf16 v[64:79], v[68:71], v[108:111], v[226:241]
	v_mov_b32_e32 v192, v124
	v_mfma_f32_32x32x16_bf16 v[80:95], v[112:115], v[104:107], v[80:95]
	v_mfma_f32_32x32x16_bf16 v[64:79], v[120:123], v[104:107], v[64:79]
	ds_read_b128 v[112:115], v140
	ds_read_b128 v[120:123], v140 offset:8192
	s_waitcnt lgkmcnt(0)
	v_mfma_f32_32x32x16_bf16 v[80:95], v[112:115], v[100:103], v[80:95]
	v_mfma_f32_32x32x16_bf16 v[64:79], v[120:123], v[100:103], v[64:79]
	ds_read_b128 v[112:115], v139
	ds_read_b128 v[120:123], v139 offset:8192
	s_waitcnt lgkmcnt(0)
	v_mfma_f32_32x32x16_bf16 v[80:95], v[112:115], v[96:99], v[80:95]
	v_add_f32_e32 v112, v162, v151
	v_add_f32_e32 v243, v167, v152
	v_add_f32_e32 v244, v169, v153
	v_add_f32_e32 v245, v170, v154
	v_add_f32_e32 v246, v171, v155
	v_add_f32_e32 v247, v172, v156
	v_add_f32_e32 v251, v173, v158
	v_add_f32_e32 v252, v188, v159
	v_add_f32_e32 v112, v191, v112
	v_add_f32_e32 v243, v126, v243
	v_add_f32_e32 v244, v127, v244
	v_add_f32_e32 v245, v128, v245
	v_add_f32_e32 v246, v129, v246
	v_add_f32_e32 v247, v143, v247
	v_add_f32_e32 v251, v144, v251
	v_add_f32_e32 v252, v145, v252
	v_add_f32_e32 v112, v146, v112
	v_add_f32_e32 v243, v147, v243
	v_mfma_f32_32x32x16_bf16 v[64:79], v[120:123], v[96:99], v[64:79]
	v_add_f32_e32 v244, v148, v244
	v_add_f32_e32 v245, v149, v245
	v_add_f32_e32 v246, v150, v246
	v_add_f32_e32 v247, v189, v247
	v_add_f32_e32 v251, v190, v251
	v_add_f32_e32 v252, v192, v252
	v_add_f32_e32 v112, v112, v243
	v_add_f32_e32 v244, v244, v245
	v_add_f32_e32 v246, v246, v247
	v_add_f32_e32 v251, v251, v252
	v_add_f32_e32 v112, v112, v244
	v_add_f32_e32 v246, v246, v251
	v_add_f32_e32 v120, v112, v246
	v_mov_b32_e32 v121, v120
	v_cvt_pk_bf16_f32 v112, v151, v152
	v_cvt_pk_bf16_f32 v113, v153, v154
	v_cvt_pk_bf16_f32 v114, v155, v156
	v_cvt_pk_bf16_f32 v115, v158, v159
	s_nop 1
	v_permlane32_swap_b32_e32 v120, v121
	v_cvt_pk_bf16_f32 v122, v162, v167
	v_cvt_pk_bf16_f32 v123, v169, v170
	v_cvt_pk_bf16_f32 v124, v171, v172
	v_cvt_pk_bf16_f32 v125, v173, v188
	v_cvt_pk_bf16_f32 v126, v191, v126
	v_cvt_pk_bf16_f32 v127, v127, v128
	v_cvt_pk_bf16_f32 v128, v129, v143
	v_cvt_pk_bf16_f32 v129, v144, v145
	v_cvt_pk_bf16_f32 v144, v146, v147
	v_cvt_pk_bf16_f32 v145, v148, v149
	v_cvt_pk_bf16_f32 v146, v150, v189
	v_cvt_pk_bf16_f32 v147, v190, v192
	s_nop 0
	s_add_u32 s4, s14, 0x20000
	s_addc_u32 s5, s15, 0
	s_add_u32 s56, s14, 0x2020000
	s_mov_b32 m0, s16
	s_addc_u32 s57, s15, 0
	s_add_i32 s55, s42, s55
	s_nop 0
	global_load_lds_dwordx4 v134, s[4:5]
	s_mov_b32 m0, s17
	s_nop 0
	global_load_lds_dwordx4 v135, s[4:5]
	s_mov_b32 m0, s55
	s_nop 0
	global_load_lds_dwordx4 v136, s[56:57]
	s_add_i32 m0, s55, 0x2000
	s_nop 0
	global_load_lds_dwordx4 v137, s[56:57]
	v_lshl_add_u32 v143, s54, 14, v133
	ds_read_b64_tr_b16 v[148:149], v143 offset:0
	ds_read_b64_tr_b16 v[150:151], v143 offset:0x800
	ds_read_b64_tr_b16 v[152:153], v143 offset:0x1000
	ds_read_b64_tr_b16 v[154:155], v143 offset:0x1800
	ds_read_b64_tr_b16 v[170:171], v143 offset:0x2000
	ds_read_b64_tr_b16 v[172:173], v143 offset:0x2800
	ds_read_b64_tr_b16 v[188:189], v143 offset:0x3000
	ds_read_b64_tr_b16 v[190:191], v143 offset:0x3800
	s_nop 0
	s_waitcnt lgkmcnt(6)
; #define SBAR() __builtin_amdgcn_sched_barrier(0)
; template <int MLA>
; __device__ __forceinline__ void partialSM(f32x16& p0, f32x16& p1, float& m_reg, float& mn, float& alpha) {
;     ...
;   float pmax = p0[0];
; #pragma unroll
;   for (int r = 1; r < 16; ++r) pmax = fmaxf(pmax, p0[r]);
; #pragma unroll
;   for (int r = 0; r < 16; ++r) pmax = fmaxf(pmax, p1[r]);
;   { auto rr = __builtin_amdgcn_permlane32_swap(__float_as_uint(pmax), __float_as_uint(pmax), false, false);
;     pmax = fmaxf(__uint_as_float(rr[0]), __uint_as_float(rr[1])); }
;   if (__builtin_expect(__all(pmax - m_reg <= THR / SCALE), 1)) { mn = m_reg; alpha = 1.f; }
;   else { mn = fmaxf(m_reg, pmax); alpha = __builtin_amdgcn_exp2f((m_reg - mn) * C); m_reg = mn; }
; template <int D0> __device__ __forceinline__ void pv_one_t(f32x16& od, int vb, bf16x8 pa0, bf16x8 pa1, bf16x8 pa2, bf16x8 pa3) {
;   const s16x4 l0 = tr_read<v_rd_off(D0, 0, 0)>(vb), h0 = tr_read<v_rd_off(D0, 0, 1)>(vb), l1 = tr_read<v_rd_off(D0, 1, 0)>(vb), h1 = tr_read<v_rd_off(D0, 1, 1)>(vb);
;   const s16x4 l2 = tr_read<v_rd_off(D0, 2, 0)>(vb), h2 = tr_read<v_rd_off(D0, 2, 1)>(vb), l3 = tr_read<v_rd_off(D0, 3, 0)>(vb), h3 = tr_read<v_rd_off(D0, 3, 1)>(vb);
;   asm volatile("s_waitcnt lgkmcnt(0)" ::: "memory"); SBAR();
;     ...
;   od = __builtin_amdgcn_mfma_f32_32x32x16_bf16(PK(l0, h0), pa0, od, 0, 0, 0);
;   od = __builtin_amdgcn_mfma_f32_32x32x16_bf16(PK(l1, h1), pa1, od, 0, 0, 0);
;   od = __builtin_amdgcn_mfma_f32_32x32x16_bf16(PK(l2, h2), pa2, od, 0, 0, 0);
;   od = __builtin_amdgcn_mfma_f32_32x32x16_bf16(PK(l3, h3), pa3, od, 0, 0, 0);
;     ...
; }
	v_mfma_f32_32x32x16_bf16 v[32:47], v[148:151], v[112:115], v[32:47]
	ds_read_b64_tr_b16 v[148:149], v143 offset:0x200
	ds_read_b64_tr_b16 v[150:151], v143 offset:0xa00
	s_waitcnt lgkmcnt(6)
	v_mfma_f32_32x32x16_bf16 v[32:47], v[152:155], v[122:125], v[32:47]
	ds_read_b64_tr_b16 v[152:153], v143 offset:0x1200
	ds_read_b64_tr_b16 v[154:155], v143 offset:0x1a00
	s_waitcnt lgkmcnt(6)
	v_mfma_f32_32x32x16_bf16 v[32:47], v[170:173], v[126:129], v[32:47]
	ds_read_b64_tr_b16 v[170:171], v143 offset:0x2200
	ds_read_b64_tr_b16 v[172:173], v143 offset:0x2a00
	s_waitcnt lgkmcnt(6)
	v_mfma_f32_32x32x16_bf16 v[32:47], v[188:191], v[144:147], v[32:47]
	ds_read_b64_tr_b16 v[188:189], v143 offset:0x3200
	ds_read_b64_tr_b16 v[190:191], v143 offset:0x3a00
	s_waitcnt lgkmcnt(6)
	v_mfma_f32_32x32x16_bf16 v[48:63], v[148:151], v[112:115], v[48:63]
	ds_read_b64_tr_b16 v[148:149], v143 offset:0x400
	ds_read_b64_tr_b16 v[150:151], v143 offset:0xc00
	s_waitcnt lgkmcnt(6)
	v_mfma_f32_32x32x16_bf16 v[48:63], v[152:155], v[122:125], v[48:63]
	ds_read_b64_tr_b16 v[152:153], v143 offset:0x1400
	ds_read_b64_tr_b16 v[154:155], v143 offset:0x1c00
	s_waitcnt lgkmcnt(6)
	v_mfma_f32_32x32x16_bf16 v[48:63], v[170:173], v[126:129], v[48:63]
	ds_read_b64_tr_b16 v[170:171], v143 offset:0x2400
	ds_read_b64_tr_b16 v[172:173], v143 offset:0x2c00
	s_waitcnt lgkmcnt(6)
	v_mfma_f32_32x32x16_bf16 v[48:63], v[188:191], v[144:147], v[48:63]
	ds_read_b64_tr_b16 v[188:189], v143 offset:0x3400
	ds_read_b64_tr_b16 v[190:191], v143 offset:0x3c00
	s_waitcnt lgkmcnt(6)
	v_mfma_f32_32x32x16_bf16 v[16:31], v[148:151], v[112:115], v[16:31]
	ds_read_b64_tr_b16 v[148:149], v143 offset:0x600
	ds_read_b64_tr_b16 v[150:151], v143 offset:0xe00
	s_waitcnt lgkmcnt(6)
	v_mfma_f32_32x32x16_bf16 v[16:31], v[152:155], v[122:125], v[16:31]
	ds_read_b64_tr_b16 v[152:153], v143 offset:0x1600
	ds_read_b64_tr_b16 v[154:155], v143 offset:0x1e00
	s_waitcnt lgkmcnt(6)
	v_mfma_f32_32x32x16_bf16 v[16:31], v[170:173], v[126:129], v[16:31]
	ds_read_b64_tr_b16 v[170:171], v143 offset:0x2600
	ds_read_b64_tr_b16 v[172:173], v143 offset:0x2e00
	s_waitcnt lgkmcnt(6)
	v_mfma_f32_32x32x16_bf16 v[16:31], v[188:191], v[144:147], v[16:31]
	ds_read_b64_tr_b16 v[188:189], v143 offset:0x3600
	ds_read_b64_tr_b16 v[190:191], v143 offset:0x3e00
	s_waitcnt lgkmcnt(6)
	v_mfma_f32_32x32x16_bf16 v[0:15], v[148:151], v[112:115], v[0:15]
	v_max_f32_e32 v112, v80, v81
	v_max3_f32 v112, v112, v82, v83
	v_max3_f32 v112, v112, v84, v85
	v_max3_f32 v112, v112, v86, v87
	v_max3_f32 v112, v112, v88, v89
	v_max3_f32 v112, v112, v90, v91
	v_max3_f32 v112, v112, v92, v93
	s_waitcnt lgkmcnt(4)
	v_mfma_f32_32x32x16_bf16 v[0:15], v[152:155], v[122:125], v[0:15]
	v_max3_f32 v112, v112, v94, v95
	v_max3_f32 v112, v112, v64, v65
	v_max3_f32 v112, v112, v66, v67
	v_max3_f32 v112, v112, v68, v69
	v_max3_f32 v112, v112, v70, v71
	v_max3_f32 v112, v112, v72, v73
	v_max3_f32 v112, v112, v74, v75
	v_max3_f32 v112, v112, v76, v77
	s_waitcnt lgkmcnt(2)
	v_mfma_f32_32x32x16_bf16 v[0:15], v[170:173], v[126:129], v[0:15]
	v_max3_f32 v112, v112, v78, v79
	v_mov_b32_e32 v113, v112
	s_nop 1
	v_permlane32_swap_b32_e32 v112, v113
	v_max_f32_e32 v112, v112, v113
	v_cmp_nge_f32_e32 vcc, s70, v112
	s_waitcnt lgkmcnt(0)
	v_mfma_f32_32x32x16_bf16 v[0:15], v[188:191], v[144:147], v[0:15]
	s_waitcnt vmcnt(0) lgkmcnt(0)
	s_barrier
	s_cbranch_vccnz .Lrare_d2
	v_mov_b32_e32 v112, 1.0
